# stack10: stack9 + P5 C-operand splat with v_mov_b64 (8 instead of 15 moves per half-step)
# speedup vs baseline: 1.0004x; 1.0004x over previous
.LBB0_1802:
	s_add_i32 s2, s83, 3
	s_add_i32 s94, s83, 2
	s_min_i32 s2, s2, s97
	s_min_i32 s3, s94, s97
	s_mul_i32 s2, s2, 0xf8000
	s_mul_i32 s3, s3, 0xf8000
	v_add_u32_e32 v2, s2, v216
	s_waitcnt vmcnt(0)
	ds_write_b128 v231, v[146:149]
	ds_write_b128 v231, v[150:153] offset:27648
	v_add_u32_e32 v8, s3, v216
	global_load_dwordx4 v[4:7], v2, s[84:85]
	s_nop 0
	global_load_dwordx4 v[8:11], v8, s[84:85] offset:128
	ds_read_b128 v[22:25], v233 offset:9248
	ds_read_b128 v[26:29], v233 offset:13824
	ds_read_b128 v[30:33], v233 offset:13856
	s_add_i32 s2, s83, 1
	s_lshl_b32 s95, 1, s2
	v_and_b32_e32 v12, s95, v155
	v_cmp_ne_u32_e64 s[72:73], 0, v12
	s_andn2_b64 vcc, exec, s[0:1]
	s_mov_b64 s[0:1], -1
	v_cndmask_b32_e64 v130, v232, v20, s[72:73]
	v_mov_b32_e32 v131, v130
	v_mov_b64_e32 v[132:133], v[130:131]
	v_mov_b64_e32 v[134:135], v[130:131]
	v_mov_b64_e32 v[136:137], v[130:131]
	v_mov_b64_e32 v[138:139], v[130:131]
	v_mov_b64_e32 v[140:141], v[130:131]
	v_mov_b64_e32 v[142:143], v[130:131]
	v_mov_b64_e32 v[144:145], v[130:131]
	s_cbranch_vccz .LBB0_1804
	ds_read_b128 v[12:15], v233 offset:9216
	s_mov_b64 s[0:1], 0
	s_waitcnt lgkmcnt(0)
	v_mfma_f32_32x32x16_bf16 v[66:81], v[12:15], v[206:209], v[130:145]
	ds_read_b128 v[12:15], v233 offset:13824
	s_waitcnt lgkmcnt(0)
	v_mfma_f32_32x32x16_bf16 v[82:97], v[12:15], v[206:209], v[130:145]
	ds_read_b128 v[12:15], v233 offset:9248
	s_waitcnt lgkmcnt(0)
	v_mfma_f32_32x32x16_bf16 v[66:81], v[12:15], v[202:205], v[66:81]
	ds_read_b128 v[12:15], v233 offset:13856
	s_waitcnt lgkmcnt(0)
	v_mfma_f32_32x32x16_bf16 v[82:97], v[12:15], v[202:205], v[82:97]
	ds_read_b128 v[12:15], v233 offset:9280
	s_waitcnt lgkmcnt(0)
	v_mfma_f32_32x32x16_bf16 v[66:81], v[12:15], v[198:201], v[66:81]
	ds_read_b128 v[12:15], v233 offset:13888
	s_waitcnt lgkmcnt(0)
	v_mfma_f32_32x32x16_bf16 v[82:97], v[12:15], v[198:201], v[82:97]
	ds_read_b128 v[12:15], v233 offset:9312
	s_waitcnt lgkmcnt(0)
	v_mfma_f32_32x32x16_bf16 v[66:81], v[12:15], v[194:197], v[66:81]
	ds_read_b128 v[12:15], v233 offset:13920
	s_waitcnt lgkmcnt(0)
	v_mfma_f32_32x32x16_bf16 v[82:97], v[12:15], v[194:197], v[82:97]

.LBB0_1807:
	s_cmp_lg_u64 s[72:73], 0
	s_waitcnt lgkmcnt(0)
	s_barrier
	s_cselect_b64 s[0:1], -1, 0
	s_cmp_eq_u64 s[72:73], 0
	v_lshl_add_u64 v[12:13], s[84:85], 0, v[2:3]
	s_cselect_b64 s[86:87], -1, 0
	s_cmp_gt_i32 s94, s97
	s_cbranch_scc1 .LBB0_1814
	s_waitcnt vmcnt(0)
	ds_write_b128 v231, v[4:7] offset:9216
	ds_write_b128 v231, v[8:11] offset:18432
	s_add_i32 s0, s83, 4
	s_min_i32 s0, s0, s97
	s_mul_i32 s0, s0, 0xf8000
	v_add_u32_e32 v2, s0, v216
	global_load_dwordx4 v[146:149], v2, s[84:85]
	global_load_dwordx4 v[150:153], v[12:13], off offset:128
	ds_read_b128 v[22:25], v233 offset:32
	ds_read_b128 v[26:29], v233 offset:4608
	ds_read_b128 v[30:33], v233 offset:4640
	s_and_b32 s72, s94, 30
	s_cmp_eq_u32 s72, 0
	s_cselect_b64 vcc, -1, 0
	s_cmp_eq_u32 s83, 30
	s_cselect_b64 s[0:1], -1, 0
	s_cmp_eq_u32 s83, 62
	s_cselect_b64 s[2:3], -1, 0
	v_cndmask_b32_e64 v2, v213, v212, s[2:3]
	v_cndmask_b32_e64 v2, v2, v211, s[0:1]
	v_cndmask_b32_e32 v155, v155, v2, vcc
	v_lshrrev_b32_e32 v2, s72, v155
	v_and_b32_e32 v2, 1, v2
	v_cmp_eq_u32_e32 vcc, 1, v2
	v_bfe_u32 v12, v155, s72, 1
	v_cmp_ne_u32_e64 s[72:73], 0, v12
	v_cndmask_b32_e32 v130, v232, v20, vcc
	v_mov_b32_e32 v131, v130
	v_mov_b64_e32 v[132:133], v[130:131]
	v_mov_b64_e32 v[134:135], v[130:131]
	v_mov_b64_e32 v[136:137], v[130:131]
	v_mov_b64_e32 v[138:139], v[130:131]
	v_mov_b64_e32 v[140:141], v[130:131]
	v_mov_b64_e32 v[142:143], v[130:131]
	v_mov_b64_e32 v[144:145], v[130:131]
	s_mov_b64 s[0:1], -1
	s_and_b64 vcc, exec, s[86:87]
	s_cbranch_vccz .LBB0_1810
	ds_read_b128 v[12:15], v233
	s_mov_b64 s[0:1], 0
	s_waitcnt lgkmcnt(0)
	v_mfma_f32_32x32x16_bf16 v[98:113], v[12:15], v[206:209], v[130:145]
	ds_read_b128 v[12:15], v233 offset:4608
	s_waitcnt lgkmcnt(0)
	v_mfma_f32_32x32x16_bf16 v[114:129], v[12:15], v[206:209], v[130:145]
	ds_read_b128 v[12:15], v233 offset:32
	s_waitcnt lgkmcnt(0)
	v_mfma_f32_32x32x16_bf16 v[98:113], v[12:15], v[202:205], v[98:113]
	ds_read_b128 v[12:15], v233 offset:4640
	s_waitcnt lgkmcnt(0)
	v_mfma_f32_32x32x16_bf16 v[114:129], v[12:15], v[202:205], v[114:129]
	ds_read_b128 v[12:15], v233 offset:64
	s_waitcnt lgkmcnt(0)
	v_mfma_f32_32x32x16_bf16 v[98:113], v[12:15], v[198:201], v[98:113]
	ds_read_b128 v[12:15], v233 offset:4672
	s_waitcnt lgkmcnt(0)
	v_mfma_f32_32x32x16_bf16 v[114:129], v[12:15], v[198:201], v[114:129]
	ds_read_b128 v[12:15], v233 offset:96
	s_waitcnt lgkmcnt(0)
	v_mfma_f32_32x32x16_bf16 v[98:113], v[12:15], v[194:197], v[98:113]
	ds_read_b128 v[12:15], v233 offset:4704
	s_waitcnt lgkmcnt(0)
	v_mfma_f32_32x32x16_bf16 v[114:129], v[12:15], v[194:197], v[114:129]
